# FFN1 k-loop: counted lgkmcnt waits per MFMA group (each group waits only for the fragment it consumes) instead of lgkmcnt(0) per k-step
# speedup vs baseline: 1.0025x; 1.0023x over previous
.LBB0_957:
	s_setprio 3
	ds_read_b128 v[130:133], v141 offset:33792
	ds_read_b128 v[142:145], v141 offset:35840
	ds_read_b128 v[146:149], v141 offset:37888
	ds_read_b128 v[150:153], v141 offset:39936
	ds_read_b128 v[154:157], v140 offset:1024
	ds_read_b128 v[158:161], v140 offset:3072
	ds_read_b128 v[174:177], v140 offset:5120
	ds_read_b128 v[186:189], v140 offset:7168
	ds_read_b128 v[190:193], v140 offset:9216
	s_waitcnt lgkmcnt(4)
	v_mfma_f32_16x16x32_bf16 v[126:129], v[130:133], v[154:157], v[126:129]
	v_mfma_f32_16x16x32_bf16 v[122:125], v[142:145], v[154:157], v[122:125]
	v_mfma_f32_16x16x32_bf16 v[118:121], v[146:149], v[154:157], v[118:121]
	v_mfma_f32_16x16x32_bf16 v[114:117], v[150:153], v[154:157], v[114:117]
	ds_read_b128 v[154:157], v140 offset:11264
	s_waitcnt lgkmcnt(4)
	v_mfma_f32_16x16x32_bf16 v[110:113], v[130:133], v[158:161], v[110:113]
	v_mfma_f32_16x16x32_bf16 v[106:109], v[142:145], v[158:161], v[106:109]
	v_mfma_f32_16x16x32_bf16 v[102:105], v[146:149], v[158:161], v[102:105]
	v_mfma_f32_16x16x32_bf16 v[98:101], v[150:153], v[158:161], v[98:101]
	ds_read_b128 v[158:161], v140 offset:13312
	s_waitcnt lgkmcnt(4)
	v_mfma_f32_16x16x32_bf16 v[94:97], v[130:133], v[174:177], v[94:97]
	v_mfma_f32_16x16x32_bf16 v[90:93], v[142:145], v[174:177], v[90:93]
	v_mfma_f32_16x16x32_bf16 v[86:89], v[146:149], v[174:177], v[86:89]
	v_mfma_f32_16x16x32_bf16 v[82:85], v[150:153], v[174:177], v[82:85]
	ds_read_b128 v[174:177], v140 offset:15360
	s_waitcnt lgkmcnt(4)
	v_mfma_f32_16x16x32_bf16 v[78:81], v[130:133], v[186:189], v[78:81]
	v_mfma_f32_16x16x32_bf16 v[74:77], v[142:145], v[186:189], v[74:77]
	v_mfma_f32_16x16x32_bf16 v[70:73], v[146:149], v[186:189], v[70:73]
	v_mfma_f32_16x16x32_bf16 v[66:69], v[150:153], v[186:189], v[66:69]
	s_waitcnt lgkmcnt(3)
	v_mfma_f32_16x16x32_bf16 v[62:65], v[130:133], v[190:193], v[62:65]
	v_mfma_f32_16x16x32_bf16 v[58:61], v[142:145], v[190:193], v[58:61]
	v_mfma_f32_16x16x32_bf16 v[54:57], v[146:149], v[190:193], v[54:57]
	v_mfma_f32_16x16x32_bf16 v[50:53], v[150:153], v[190:193], v[50:53]
	s_waitcnt lgkmcnt(2)
	v_mfma_f32_16x16x32_bf16 v[46:49], v[130:133], v[154:157], v[46:49]
	v_mfma_f32_16x16x32_bf16 v[42:45], v[142:145], v[154:157], v[42:45]
	v_mfma_f32_16x16x32_bf16 v[38:41], v[146:149], v[154:157], v[38:41]
	v_mfma_f32_16x16x32_bf16 v[34:37], v[150:153], v[154:157], v[34:37]
	s_waitcnt lgkmcnt(1)
	v_mfma_f32_16x16x32_bf16 v[30:33], v[130:133], v[158:161], v[30:33]
	v_mfma_f32_16x16x32_bf16 v[26:29], v[142:145], v[158:161], v[26:29]
	v_mfma_f32_16x16x32_bf16 v[22:25], v[146:149], v[158:161], v[22:25]
	v_mfma_f32_16x16x32_bf16 v[18:21], v[150:153], v[158:161], v[18:21]
	s_waitcnt lgkmcnt(0)
	v_mfma_f32_16x16x32_bf16 v[14:17], v[130:133], v[174:177], v[14:17]
	v_mfma_f32_16x16x32_bf16 v[10:13], v[142:145], v[174:177], v[10:13]
	v_mfma_f32_16x16x32_bf16 v[6:9], v[146:149], v[174:177], v[6:9]
	v_mfma_f32_16x16x32_bf16 v[2:5], v[150:153], v[174:177], v[2:5]
	s_setprio 0
	s_add_i32 s77, s77, 64
	s_add_i32 s76, s76, 0x10000
	s_cmpk_eq_i32 s77, 0x3c0
	s_cbranch_scc1 .Lpf_f1_last
	s_waitcnt vmcnt(1)
	s_barrier
	s_branch .Lpf_f1_cont

.Lpf_skip_f1a:
.LBB0_960:
	s_add_i32 s91, s89, 0x400
	v_add_u32_e32 v131, s91, v137
	v_add_u32_e32 v133, s91, v138
	s_setprio 3
	v_add_u32_e32 v141, v133, v136
	ds_read_b128 v[142:145], v141 offset:32768
	ds_read_b128 v[146:149], v141 offset:34816
	ds_read_b128 v[150:153], v141 offset:36864
	ds_read_b128 v[154:157], v141 offset:38912
	v_add_u32_e32 v140, v131, v136
	ds_read_b128 v[158:161], v140
	ds_read_b128 v[174:177], v140 offset:2048
	ds_read_b128 v[186:189], v140 offset:4096
	ds_read_b128 v[190:193], v140 offset:6144
	ds_read_b128 v[194:197], v140 offset:8192
	s_waitcnt lgkmcnt(4)
	v_mfma_f32_16x16x32_bf16 v[126:129], v[142:145], v[158:161], v[126:129]
	v_mfma_f32_16x16x32_bf16 v[122:125], v[146:149], v[158:161], v[122:125]
	v_mfma_f32_16x16x32_bf16 v[118:121], v[150:153], v[158:161], v[118:121]
	v_mfma_f32_16x16x32_bf16 v[114:117], v[154:157], v[158:161], v[114:117]
	ds_read_b128 v[158:161], v140 offset:10240
	s_waitcnt lgkmcnt(4)
	v_mfma_f32_16x16x32_bf16 v[110:113], v[142:145], v[174:177], v[110:113]
	v_mfma_f32_16x16x32_bf16 v[106:109], v[146:149], v[174:177], v[106:109]
	v_mfma_f32_16x16x32_bf16 v[102:105], v[150:153], v[174:177], v[102:105]
	v_mfma_f32_16x16x32_bf16 v[98:101], v[154:157], v[174:177], v[98:101]
	ds_read_b128 v[174:177], v140 offset:12288
	s_waitcnt lgkmcnt(4)
	v_mfma_f32_16x16x32_bf16 v[94:97], v[142:145], v[186:189], v[94:97]
	v_mfma_f32_16x16x32_bf16 v[90:93], v[146:149], v[186:189], v[90:93]
	v_mfma_f32_16x16x32_bf16 v[86:89], v[150:153], v[186:189], v[86:89]
	v_mfma_f32_16x16x32_bf16 v[82:85], v[154:157], v[186:189], v[82:85]
	ds_read_b128 v[186:189], v140 offset:14336
	s_waitcnt lgkmcnt(4)
	v_mfma_f32_16x16x32_bf16 v[78:81], v[142:145], v[190:193], v[78:81]
	v_mfma_f32_16x16x32_bf16 v[74:77], v[146:149], v[190:193], v[74:77]
	v_mfma_f32_16x16x32_bf16 v[70:73], v[150:153], v[190:193], v[70:73]
	v_mfma_f32_16x16x32_bf16 v[66:69], v[154:157], v[190:193], v[66:69]
	s_waitcnt lgkmcnt(3)
	v_mfma_f32_16x16x32_bf16 v[62:65], v[142:145], v[194:197], v[62:65]
	v_mfma_f32_16x16x32_bf16 v[58:61], v[146:149], v[194:197], v[58:61]
	v_mfma_f32_16x16x32_bf16 v[54:57], v[150:153], v[194:197], v[54:57]
	v_mfma_f32_16x16x32_bf16 v[50:53], v[154:157], v[194:197], v[50:53]
	s_waitcnt lgkmcnt(2)
	v_mfma_f32_16x16x32_bf16 v[46:49], v[142:145], v[158:161], v[46:49]
	v_mfma_f32_16x16x32_bf16 v[42:45], v[146:149], v[158:161], v[42:45]
	v_mfma_f32_16x16x32_bf16 v[38:41], v[150:153], v[158:161], v[38:41]
	v_mfma_f32_16x16x32_bf16 v[34:37], v[154:157], v[158:161], v[34:37]
	s_waitcnt lgkmcnt(1)
	v_mfma_f32_16x16x32_bf16 v[30:33], v[142:145], v[174:177], v[30:33]
	v_mfma_f32_16x16x32_bf16 v[26:29], v[146:149], v[174:177], v[26:29]
	v_mfma_f32_16x16x32_bf16 v[22:25], v[150:153], v[174:177], v[22:25]
	v_mfma_f32_16x16x32_bf16 v[18:21], v[154:157], v[174:177], v[18:21]
	s_waitcnt lgkmcnt(0)
	v_mfma_f32_16x16x32_bf16 v[14:17], v[142:145], v[186:189], v[14:17]
	v_mfma_f32_16x16x32_bf16 v[10:13], v[146:149], v[186:189], v[10:13]
	v_mfma_f32_16x16x32_bf16 v[6:9], v[150:153], v[186:189], v[6:9]
	v_mfma_f32_16x16x32_bf16 v[2:5], v[154:157], v[186:189], v[2:5]
	s_setprio 0
	s_andn2_b64 vcc, exec, s[94:95]
	s_cbranch_vccnz .LBB0_957
	s_xor_b32 s89, s89, 0x10000
	v_add_u32_e32 v146, s89, v172
	v_add_u32_e32 v131, 0x8000, v146
	v_lshlrev_b64 v[142:143], 1, v[0:1]
	v_readfirstlane_b32 s89, v146
	v_lshl_add_u64 v[144:145], s[86:87], 0, v[142:143]
	s_mov_b32 m0, s89
	v_readfirstlane_b32 s89, v131
	v_mov_b32_e32 v135, v1
	v_add_u32_e32 v0, 0x2000, v146
	global_load_lds_dwordx4 v[144:145], off
	v_lshl_add_u64 v[142:143], s[96:97], 0, v[142:143]
	s_mov_b32 m0, s89
	v_lshlrev_b64 v[134:135], 1, v[134:135]
	v_readfirstlane_b32 s89, v0
	v_add_u32_e32 v0, 0xa000, v146
	global_load_lds_dwordx4 v[142:143], off
	v_lshl_add_u64 v[142:143], s[86:87], 0, v[134:135]
	s_mov_b32 m0, s89
	v_readfirstlane_b32 s89, v0
	v_mov_b32_e32 v133, v1
	v_add_u32_e32 v0, 0x4000, v146
	global_load_lds_dwordx4 v[142:143], off
	v_lshl_add_u64 v[134:135], s[96:97], 0, v[134:135]
	s_mov_b32 m0, s89
	v_lshlrev_b64 v[132:133], 1, v[132:133]
	v_readfirstlane_b32 s89, v0
	v_add_u32_e32 v0, 0xc000, v146
	global_load_lds_dwordx4 v[134:135], off
	v_lshl_add_u64 v[134:135], s[86:87], 0, v[132:133]
	s_mov_b32 m0, s89
	v_readfirstlane_b32 s89, v0
	v_mov_b32_e32 v131, v1
	v_add_u32_e32 v0, 0x6000, v146
	global_load_lds_dwordx4 v[134:135], off
	v_lshl_add_u64 v[132:133], s[96:97], 0, v[132:133]
	s_mov_b32 m0, s89
	v_lshlrev_b64 v[130:131], 1, v[130:131]
	v_readfirstlane_b32 s89, v0
	v_add_u32_e32 v0, 0xe000, v146
	global_load_lds_dwordx4 v[132:133], off
	v_lshl_add_u64 v[132:133], s[86:87], 0, v[130:131]
	s_mov_b32 m0, s89
	v_readfirstlane_b32 s89, v0
	global_load_lds_dwordx4 v[132:133], off
	v_lshl_add_u64 v[130:131], s[96:97], 0, v[130:131]
	s_mov_b32 m0, s89
	s_nop 0
	global_load_lds_dwordx4 v[130:131], off
	s_cmpk_eq_i32 s77, 0x380
	s_cbranch_scc1 .Lpf_skip_f1b
	v_readfirstlane_b32 s14, v162
	v_lshrrev_b32_e32 v202, 7, v162
	v_bfe_u32 v203, v162, 4, 2
	v_lshl_add_u32 v202, v203, 2, v202
	v_and_b32_e32 v203, 15, v162
	v_lshl_add_u32 v202, v202, 4, v203
	s_lshl_b32 s15, s77, 1
	s_addk_i32 s15, 0x100
	v_lshl_add_u32 v202, v202, 11, s15
	s_bitcmp1_b32 s14, 6
	s_cselect_b32 s16, s96, s86
	s_cselect_b32 s17, s97, s87
	global_load_dword v204, v202, s[16:17]
